# P4 work-queue reorder: fox-short units before ssd_out units
# baseline (speedup 1.0000x reference)
; DI void norm_unit(const Params& p, int layer, int half, int nu, int tid) { norm_rows(p, layer, half * HROWS + nu * 64, 64, 0, 8, tid); }
; #define otid() otid_(wbase)
; __global__ void __launch_bounds__(NTHR) mega(Params p) {
;     ...
;           __syncthreads();
;           if (otid() == 0) s_unit = atomicAdd(my, 1);
;           __syncthreads();
;           const int u0 = s_unit;
;           const int n_fill = (hf == 1) ? 256 : 0;
;           int u = u0;
;           if (u >= 1344 + n_fill) break;
;           if (u >= 448 && u < 448 + n_fill) { norm_unit(p, layer + 1, 0, u - 448, otid()); continue; }
;           if (u >= 448) u -= n_fill;
;           const bool needs = (u >= 448 && u < 576) || (u >= 832);
;           if (needs && !dep_ok) {
.LBB0_417:
	s_or_b64 exec, exec, s[0:1]
	s_waitcnt lgkmcnt(0)
	s_barrier
	ds_read_b32 v0, v161 offset:16
	v_readlane_b32 s0, v254, 47
	s_waitcnt lgkmcnt(0)
	v_readfirstlane_b32 s23, v0
	v_cmp_le_i32_e64 s[0:1], s0, v0
	s_and_b64 vcc, exec, s[0:1]
	s_cbranch_vccnz .LBB0_412
	v_writelane_b32 v254, s0, 57
	s_cmpk_gt_i32 s23, 0x1bf
	s_nop 0
	v_writelane_b32 v254, s1, 58
	s_cselect_b64 s[0:1], -1, 0
	v_readlane_b32 s2, v254, 48
	s_cmp_lt_i32 s23, s2
	s_cselect_b64 s[4:5], -1, 0
	s_and_b64 s[4:5], s[0:1], s[4:5]
	s_andn2_b64 vcc, exec, s[4:5]
	s_mov_b64 s[4:5], -1
	s_cbranch_vccz .LBB0_622
	s_and_b64 s[0:1], s[0:1], exec
	v_readlane_b32 s0, v254, 25
	s_cselect_b32 s0, s0, 0
	s_nop 0
	v_writelane_b32 v254, s0, 59
	s_sub_i32 s0, s23, s0
	s_add_i32 s16, s0, 0xfffffd40
	v_writelane_b32 v254, s0, 60
	s_cmpk_lt_i32 s0, 0x340
	v_readlane_b32 s4, v254, 53
	s_cselect_b64 s[0:1], -1, 0
	v_readlane_b32 s5, v254, 54
	s_or_b64 s[0:1], s[0:1], s[4:5]
	s_cmpk_lt_u32 s16, 0x80
	v_cndmask_b32_e64 v0, 0, 1, s[0:1]
	v_cndmask_b32_e64 v1, 0, 1, s[4:5]
	s_cselect_b64 vcc, -1, 0
	v_cndmask_b32_e32 v0, v0, v1, vcc
	v_and_b32_e32 v0, 1, v0
	v_cmp_eq_u32_e32 vcc, 1, v0
	s_cbranch_vccnz .LBB0_431
	v_mov_b32_e32 v0, v163
	s_nop 0
	v_cmp_eq_u32_e32 vcc, 0, v0
	s_and_saveexec_b64 s[0:1], vcc
	s_cbranch_execz .LBB0_430
	s_mov_b32 s2, 0x400001
	s_branch .LBB0_423

; #define otid() otid_(wbase)
; DI void ret_out_unit(const Params& p, int hf, int bl, int c, int hd, unsigned char* shm, int tid, bool dry = false) {
;     ...
;   for (int it = 0; it < 2; ++it) {
;     const int idx = tid + it * NTHR, j = idx >> 3, dg = idx & 7;
;     const bf16_t* base = projb + (size_t)(c * 128 + j) * NP;
;     float q1[8], q2[8], k1[8], k2[8];
;     unpack8(*(const uint4*)(base + C_RQ + hd * 128 + dg * 8), q1); unpack8(*(const uint4*)(base + C_RQ + hd * 128 + 64 + dg * 8), q2);
;     unpack8(*(const uint4*)(base + C_RK + hd * 128 + dg * 8), k1); unpack8(*(const uint4*)(base + C_RK + hd * 128 + 64 + dg * 8), k2);
;     float oq1[8], oq2[8], ok1[8], ok2[8];
; #pragma unroll
;     for (int e = 0; e < 8; ++e) {
;       const float2 t = cs[j * 64 + dg * 8 + e];
;       oq1[e] = q1[e] * t.x - q2[e] * t.y; oq2[e] = q1[e] * t.y + q2[e] * t.x;
;       ok1[e] = (k1[e] * t.x - k2[e] * t.y) * 0.08838834764831845f; ok2[e] = (k1[e] * t.y + k2[e] * t.x) * 0.08838834764831845f;
;     }
;     *(uint4*)(sQ + j * LD + dg * 8) = pack8(oq1); *(uint4*)(sQ + j * LD + 64 + dg * 8) = pack8(oq2);
;     *(uint4*)(sK + j * LD + dg * 8) = pack8(ok1); *(uint4*)(sK + j * LD + 64 + dg * 8) = pack8(ok2);
;     *(uint4*)(sVt + j * LD + dg * 16) = *(const uint4*)(base + C_RV + hd * 128 + dg * 16);
;     *(uint4*)(sVt + j * LD + dg * 16 + 8) = *(const uint4*)(base + C_RV + hd * 128 + dg * 16 + 8);
; __global__ void __launch_bounds__(NTHR) mega(Params p) {
;     ...
;           if (u < 256) { fox_unit(p, hf, (u >> 3) & 1, u & 7, 31 - (u >> 4), shm, otid()); }
;           else if (u < 448) {
;             scan_unit(p, hf, u - 256, otid());
;             asm volatile("s_waitcnt vmcnt(0)" ::: "memory");
;             __syncthreads();
;             if (otid() == 0) { __builtin_amdgcn_fence(__ATOMIC_RELEASE, "agent"); asm volatile("s_waitcnt vmcnt(0)" ::: "memory"); __hip_atomic_fetch_add(dep, 1, __ATOMIC_RELAXED, __HIP_MEMORY_SCOPE_AGENT); }
;           }
;           else if (u < 576) { const int k = u - 448; ssd_out_unit(p, layer, hf, k >> 6, k & 63, shm, otid()); }
;           else if (u < 832) { const int k = u - 576 + 256; fox_unit(p, hf, (k >> 3) & 1, k & 7, 31 - (k >> 4), shm, otid()); }
;           else { const int k = u - 832; ret_out_unit(p, hf, k >> 8, (k >> 2) & 63, k & 3, shm, otid()); }
.LBB0_431:
	v_writelane_b32 v254, s4, 61
	s_nop 1
	v_writelane_b32 v254, s5, 62
	s_nop 0
	v_readlane_b32 s0, v254, 60
	s_cmpk_gt_i32 s0, 0xff
	s_mov_b64 s[0:1], -1
	s_cbranch_scc0 .LBB0_588
	v_readlane_b32 s0, v254, 60
	s_cmpk_gt_u32 s0, 0x1bf
	s_mov_b64 s[0:1], -1
	s_cbranch_scc0 .LBB0_573
	v_readlane_b32 s0, v254, 60
	s_cmpk_gt_i32 s0, 0x2bf
	s_mov_b64 s[0:1], -1
	s_cbranch_scc0 .LBB0_468
	v_readlane_b32 s0, v254, 60
	s_cmpk_gt_u32 s0, 0x33f
	s_mov_b64 s[0:1], -1
	s_cbranch_scc0 .LBB0_500
	v_readlane_b32 s0, v254, 60
	s_add_i32 s5, s0, 0xfffffcc0
	s_lshr_b32 s4, s5, 8
	s_mul_i32 s2, s4, 0x3400000
	s_bfe_u32 s7, s5, 0x60002
	s_and_b32 s6, s23, 3
	s_lshl_b64 s[0:1], s[2:3], 1
	s_add_u32 s8, s38, s0
	v_cvt_f32_ubyte0_e32 v0, s6
	s_addc_u32 s9, s39, s1
	s_lshl_b32 s0, s4, 13
	v_sub_f32_e32 v0, 0xc0a00000, v0
	s_add_i32 s0, s0, s68
	s_lshl_b32 s4, s7, 7
	v_exp_f32_e32 v0, v0
	s_or_b32 s0, s0, s4
	s_lshl_b32 s2, s0, 6
	v_mov_b32_e32 v66, v163
	s_lshl_b64 s[0:1], s[2:3], 3
	v_readlane_b32 s2, v252, 45
	s_add_u32 s0, s2, s0
	v_readlane_b32 s2, v252, 46
	v_sub_f32_e32 v32, 1.0, v0
	v_and_b32_e32 v0, 7, v66
	v_ashrrev_i32_e32 v18, 3, v66
	s_addc_u32 s1, s2, s1
	v_lshlrev_b32_e32 v20, 3, v0
	v_lshlrev_b32_e32 v160, 4, v0
	v_lshlrev_b32_e32 v12, 5, v0
	v_readlane_b32 s2, v254, 0
	v_add_u32_e32 v0, s4, v18
	v_mov_b64_e32 v[16:17], s[8:9]
	v_add_u32_e32 v19, s2, v12
	v_mad_i64_i32 v[0:1], s[8:9], v0, s65, v[16:17]
	s_lshl_b32 s2, s6, 8
	v_lshl_add_u64 v[14:15], v[0:1], 0, s[2:3]
	v_lshl_add_u64 v[4:5], v[14:15], 0, v[160:161]
	v_lshl_add_u64 v[224:225], v[14:15], 0, v[160:161]
	global_load_dwordx4 v[100:103], v[224:225], off
	global_load_dwordx4 v[104:107], v[224:225], off offset:128
	global_load_dwordx4 v[108:111], v[224:225], off offset:1024
	global_load_dwordx4 v[112:115], v[224:225], off offset:1152
	v_lshl_or_b32 v226, v18, 6, v20
	v_mov_b32_e32 v227, v161
	v_lshl_add_u64 v[226:227], v[226:227], 3, s[0:1]
	global_load_dwordx4 v[116:119], v[226:227], off offset:48
	global_load_dwordx4 v[120:123], v[226:227], off offset:32
	global_load_dwordx4 v[124:127], v[226:227], off offset:16
	global_load_dwordx4 v[128:131], v[226:227], off
	v_mov_b32_e32 v228, v12
	v_mov_b32_e32 v229, v161
	v_lshl_add_u64 v[228:229], v[14:15], 0, v[228:229]
	global_load_dwordx4 v[132:135], v[228:229], off offset:2048
	global_load_dwordx4 v[136:139], v[228:229], off offset:2064
	v_add_u32_e32 v230, 64, v18
	v_add_u32_e32 v231, s4, v230
	v_mad_i64_i32 v[232:233], s[8:9], v231, s65, v[16:17]
	v_lshl_add_u64 v[232:233], v[232:233], 0, s[2:3]
	v_lshl_add_u64 v[234:235], v[232:233], 0, v[160:161]
	global_load_dwordx4 v[140:143], v[234:235], off
	global_load_dwordx4 v[144:147], v[234:235], off offset:128
	global_load_dwordx4 v[148:151], v[234:235], off offset:1024
	global_load_dwordx4 v[152:155], v[234:235], off offset:1152
	v_lshl_or_b32 v236, v230, 6, v20
	v_mov_b32_e32 v237, v161
	v_lshl_add_u64 v[236:237], v[236:237], 3, s[0:1]
	global_load_dwordx4 v[156:159], v[236:237], off offset:48
	global_load_dwordx4 v[204:207], v[236:237], off offset:32
	global_load_dwordx4 v[208:211], v[236:237], off offset:16
	global_load_dwordx4 v[212:215], v[236:237], off
	v_mov_b32_e32 v238, v12
	v_mov_b32_e32 v239, v161
	v_lshl_add_u64 v[238:239], v[232:233], 0, v[238:239]
	global_load_dwordx4 v[216:219], v[238:239], off offset:2048
	global_load_dwordx4 v[220:223], v[238:239], off offset:2064
	v_mul_lo_u32 v67, v18, s66
	v_ashrrev_i32_e32 v73, 6, v66
	v_and_b32_e32 v74, 15, v66
	v_lshl_or_b32 v68, v73, 4, v74
	v_bfe_u32 v75, v66, 4, 2
	v_mul_u32_u24_e32 v71, 0x110, v74
	s_waitcnt vmcnt(19)
	v_mov_b32_e32 v0, v100
	v_mov_b32_e32 v1, v101
	v_mov_b32_e32 v2, v102
	v_mov_b32_e32 v3, v103
	v_lshlrev_b32_e32 v26, 16, v0
	v_and_b32_e32 v27, 0xffff0000, v0
	v_lshlrev_b32_e32 v28, 16, v1
	v_and_b32_e32 v29, 0xffff0000, v1
	v_lshlrev_b32_e32 v30, 16, v2
	v_and_b32_e32 v31, 0xffff0000, v2
	v_lshlrev_b32_e32 v21, 16, v3
	v_and_b32_e32 v13, 0xffff0000, v3
	s_waitcnt vmcnt(18)
	v_mov_b32_e32 v0, v104
	v_mov_b32_e32 v1, v105
	v_mov_b32_e32 v2, v106
	v_mov_b32_e32 v3, v107
	v_lshlrev_b32_e32 v33, 16, v0
	v_and_b32_e32 v34, 0xffff0000, v0
	v_lshlrev_b32_e32 v35, 16, v1
	v_and_b32_e32 v36, 0xffff0000, v1
	v_lshlrev_b32_e32 v37, 16, v2
	v_and_b32_e32 v38, 0xffff0000, v2
	v_lshlrev_b32_e32 v39, 16, v3
	v_and_b32_e32 v40, 0xffff0000, v3
	s_waitcnt vmcnt(17)
	v_mov_b32_e32 v0, v108
	v_mov_b32_e32 v1, v109
	v_mov_b32_e32 v2, v110
	v_mov_b32_e32 v3, v111
	v_lshlrev_b32_e32 v41, 16, v0
	v_and_b32_e32 v42, 0xffff0000, v0
	v_lshlrev_b32_e32 v43, 16, v1
	v_and_b32_e32 v44, 0xffff0000, v1
	v_lshlrev_b32_e32 v45, 16, v2
	v_and_b32_e32 v46, 0xffff0000, v2
	v_lshlrev_b32_e32 v47, 16, v3
	v_and_b32_e32 v48, 0xffff0000, v3
	s_waitcnt vmcnt(16)
	v_mov_b32_e32 v0, v112
	v_mov_b32_e32 v1, v113
	v_mov_b32_e32 v2, v114
	v_mov_b32_e32 v3, v115
	v_lshlrev_b32_e32 v49, 16, v0
	v_and_b32_e32 v50, 0xffff0000, v0
	v_lshl_or_b32 v0, v18, 6, v20
	v_lshlrev_b32_e32 v51, 16, v1
	v_and_b32_e32 v52, 0xffff0000, v1
	v_ashrrev_i32_e32 v1, 31, v0
	v_lshl_add_u64 v[22:23], v[0:1], 3, s[0:1]
	v_lshlrev_b32_e32 v53, 16, v2
	v_and_b32_e32 v54, 0xffff0000, v2
	v_lshlrev_b32_e32 v55, 16, v3
	v_and_b32_e32 v56, 0xffff0000, v3
	s_nop 0
	s_waitcnt vmcnt(12)
; DI uint4 pack8(const float* f) { uint4 r; r.x = pk2(f[0], f[1]); r.y = pk2(f[2], f[3]); r.z = pk2(f[4], f[5]); r.w = pk2(f[6], f[7]); return r; }
; DI void ret_out_unit(const Params& p, int hf, int bl, int c, int hd, unsigned char* shm, int tid, bool dry = false) {
;     ...
;     float oq1[8], oq2[8], ok1[8], ok2[8];
; #pragma unroll
;     for (int e = 0; e < 8; ++e) {
;       const float2 t = cs[j * 64 + dg * 8 + e];
;       oq1[e] = q1[e] * t.x - q2[e] * t.y; oq2[e] = q1[e] * t.y + q2[e] * t.x;
;       ok1[e] = (k1[e] * t.x - k2[e] * t.y) * 0.08838834764831845f; ok2[e] = (k1[e] * t.y + k2[e] * t.x) * 0.08838834764831845f;
;     }
;     *(uint4*)(sQ + j * LD + dg * 8) = pack8(oq1); *(uint4*)(sQ + j * LD + 64 + dg * 8) = pack8(oq2);
;     *(uint4*)(sK + j * LD + dg * 8) = pack8(ok1); *(uint4*)(sK + j * LD + 64 + dg * 8) = pack8(ok2);
;     *(uint4*)(sVt + j * LD + dg * 16) = *(const uint4*)(base + C_RV + hd * 128 + dg * 16);
;     *(uint4*)(sVt + j * LD + dg * 16 + 8) = *(const uint4*)(base + C_RV + hd * 128 + dg * 16 + 8);
	v_mov_b32_e32 v0, v116
	v_mov_b32_e32 v1, v117
	v_mov_b32_e32 v2, v118
	v_mov_b32_e32 v3, v119
	v_mov_b32_e32 v4, v120
	v_mov_b32_e32 v5, v121
	v_mov_b32_e32 v6, v122
	v_mov_b32_e32 v7, v123
	v_mov_b32_e32 v8, v124
	v_mov_b32_e32 v9, v125
	v_mov_b32_e32 v10, v126
	v_mov_b32_e32 v11, v127
	v_mov_b32_e32 v22, v128
	v_mov_b32_e32 v23, v129
	v_mov_b32_e32 v24, v130
	v_mov_b32_e32 v25, v131
	v_mul_f32_e32 v57, v23, v33
	v_fma_f32 v57, v22, v26, -v57
	v_mul_f32_e32 v26, v23, v26
	v_fmac_f32_e32 v26, v22, v33
	v_mul_f32_e32 v33, v23, v49
	v_mul_f32_e32 v23, v23, v41
	v_fmac_f32_e32 v23, v22, v49
	v_fma_f32 v33, v22, v41, -v33
	v_mul_f32_e32 v22, 0x3db504f3, v23
	v_mul_f32_e32 v23, v25, v34
	v_fma_f32 v23, v24, v27, -v23
	v_mul_f32_e32 v27, v25, v27
	v_fmac_f32_e32 v27, v24, v34
	v_mul_f32_e32 v34, v25, v50
	v_mul_f32_e32 v25, v25, v42
	v_fmac_f32_e32 v25, v24, v50
	v_fma_f32 v34, v24, v42, -v34
	v_mul_f32_e32 v24, 0x3db504f3, v25
	v_mul_f32_e32 v25, v9, v35
	v_fma_f32 v25, v8, v28, -v25
	v_mul_f32_e32 v28, v9, v28
	v_fmac_f32_e32 v28, v8, v35
	v_mul_f32_e32 v35, v9, v51
	v_mul_f32_e32 v9, v9, v43
	v_fmac_f32_e32 v9, v8, v51
	v_fma_f32 v35, v8, v43, -v35
	v_mul_f32_e32 v8, 0x3db504f3, v9
	v_mul_f32_e32 v9, v11, v36
	v_fma_f32 v9, v10, v29, -v9
	v_mul_f32_e32 v29, v11, v29
	v_fmac_f32_e32 v29, v10, v36
	v_mul_f32_e32 v36, v11, v52
	v_mul_f32_e32 v11, v11, v44
	v_fmac_f32_e32 v11, v10, v52
	v_fma_f32 v36, v10, v44, -v36
	v_mul_f32_e32 v10, 0x3db504f3, v11
	v_mul_f32_e32 v11, v5, v37
	v_fma_f32 v11, v4, v30, -v11
	v_mul_f32_e32 v30, v5, v30
	v_fmac_f32_e32 v30, v4, v37
	v_mul_f32_e32 v37, v5, v53
	v_mul_f32_e32 v5, v5, v45
	v_fmac_f32_e32 v5, v4, v53
	v_fma_f32 v37, v4, v45, -v37
	v_mul_f32_e32 v4, 0x3db504f3, v5
	v_mul_f32_e32 v5, v7, v38
	v_fma_f32 v5, v6, v31, -v5
	v_mul_f32_e32 v31, v7, v31
	v_fmac_f32_e32 v31, v6, v38
	v_mul_f32_e32 v38, v7, v54
	v_mul_f32_e32 v7, v7, v46
	v_fmac_f32_e32 v7, v6, v54
	v_fma_f32 v38, v6, v46, -v38
	v_mul_f32_e32 v6, 0x3db504f3, v7
	v_mul_f32_e32 v7, v1, v39
	v_fma_f32 v7, v0, v21, -v7
	v_mul_f32_e32 v21, v1, v21
	v_fmac_f32_e32 v21, v0, v39
	v_mul_f32_e32 v39, v1, v55
	v_mul_f32_e32 v1, v1, v47
	v_fma_f32 v39, v0, v47, -v39
	v_fmac_f32_e32 v1, v0, v55
	v_mul_f32_e32 v0, v3, v40
	v_fma_f32 v42, v2, v13, -v0
	v_mul_f32_e32 v0, v3, v56
	v_mul_f32_e32 v13, v3, v13
	v_fma_f32 v0, v2, v48, -v0
	v_fmac_f32_e32 v13, v2, v40
	v_mul_f32_e32 v40, 0x3db504f3, v0
	v_mul_f32_e32 v0, v3, v48
	v_fmac_f32_e32 v0, v2, v56
	v_mul_f32_e32 v41, 0x3db504f3, v1
	v_mul_f32_e32 v43, 0x3db504f3, v0
	v_cvt_pk_bf16_f32 v0, v57, v23
	v_cvt_pk_bf16_f32 v1, v25, v9
	v_cvt_pk_bf16_f32 v2, v11, v5
	v_cvt_pk_bf16_f32 v3, v7, v42
	v_add3_u32 v5, 32, v67, v160
	ds_write_b128 v5, v[0:3]
	v_cvt_pk_bf16_f32 v0, v26, v27
	v_cvt_pk_bf16_f32 v1, v28, v29
	v_cvt_pk_bf16_f32 v2, v30, v31
	v_cvt_pk_bf16_f32 v3, v21, v13
	v_mul_f32_e32 v33, 0x3db504f3, v33
	v_mul_f32_e32 v34, 0x3db504f3, v34
	v_mul_f32_e32 v35, 0x3db504f3, v35
	v_mul_f32_e32 v36, 0x3db504f3, v36
	v_mul_f32_e32 v37, 0x3db504f3, v37
	v_mul_f32_e32 v38, 0x3db504f3, v38
	v_mul_f32_e32 v39, 0x3db504f3, v39
	ds_write_b128 v5, v[0:3] offset:128
	v_cvt_pk_bf16_f32 v0, v33, v34
	v_cvt_pk_bf16_f32 v1, v35, v36
	v_cvt_pk_bf16_f32 v2, v37, v38
	v_cvt_pk_bf16_f32 v3, v39, v40
	v_mov_b32_e32 v13, v161
	ds_write_b128 v5, v[0:3] offset:34816
	v_cvt_pk_bf16_f32 v0, v22, v24
	v_cvt_pk_bf16_f32 v1, v8, v10
	v_cvt_pk_bf16_f32 v2, v4, v6
	v_cvt_pk_bf16_f32 v3, v41, v43
	ds_write_b128 v5, v[0:3] offset:34944
	v_lshl_add_u64 v[4:5], v[14:15], 0, v[12:13]
	v_add_u32_e32 v6, v19, v67
	s_waitcnt vmcnt(11)
	v_mov_b32_e32 v0, v132
	v_mov_b32_e32 v1, v133
	v_mov_b32_e32 v2, v134
	v_mov_b32_e32 v3, v135
	ds_write_b128 v6, v[0:3]
	s_waitcnt vmcnt(10)
	v_mov_b32_e32 v0, v136
	v_mov_b32_e32 v1, v137
	v_mov_b32_e32 v2, v138
	v_mov_b32_e32 v3, v139
	ds_write_b128 v6, v[0:3] offset:16
	v_add_u32_e32 v0, 0x200, v66
	v_ashrrev_i32_e32 v14, 3, v0
	v_add_u32_e32 v0, s4, v14
	v_mad_i64_i32 v[0:1], s[8:9], v0, s65, v[16:17]
	v_lshl_add_u64 v[4:5], v[0:1], 0, s[2:3]
	v_lshl_add_u64 v[6:7], v[4:5], 0, v[160:161]
	v_lshl_add_u64 v[4:5], v[4:5], 0, v[12:13]
	s_waitcnt vmcnt(9)
	v_mov_b32_e32 v0, v140
	v_mov_b32_e32 v1, v141
	v_mov_b32_e32 v2, v142
	v_mov_b32_e32 v3, v143
	v_lshlrev_b32_e32 v15, 16, v0
	v_and_b32_e32 v28, 0xffff0000, v0
	v_lshlrev_b32_e32 v29, 16, v1
	v_and_b32_e32 v30, 0xffff0000, v1
	v_lshlrev_b32_e32 v31, 16, v2
	v_and_b32_e32 v33, 0xffff0000, v2
	v_lshlrev_b32_e32 v34, 16, v3
	v_and_b32_e32 v35, 0xffff0000, v3
	s_waitcnt vmcnt(8)
	v_mov_b32_e32 v0, v144
	v_mov_b32_e32 v1, v145
	v_mov_b32_e32 v2, v146
	v_mov_b32_e32 v3, v147
	v_lshlrev_b32_e32 v36, 16, v0
	v_and_b32_e32 v37, 0xffff0000, v0
	v_lshlrev_b32_e32 v38, 16, v1
	v_and_b32_e32 v39, 0xffff0000, v1
	v_lshlrev_b32_e32 v40, 16, v2
	v_and_b32_e32 v41, 0xffff0000, v2
	v_lshlrev_b32_e32 v42, 16, v3
	v_and_b32_e32 v43, 0xffff0000, v3
	s_waitcnt vmcnt(7)
	v_mov_b32_e32 v0, v148
	v_mov_b32_e32 v1, v149
	v_mov_b32_e32 v2, v150
	v_mov_b32_e32 v3, v151
	v_lshlrev_b32_e32 v44, 16, v0
	v_and_b32_e32 v45, 0xffff0000, v0
	v_lshlrev_b32_e32 v46, 16, v1
	v_and_b32_e32 v47, 0xffff0000, v1
	v_lshlrev_b32_e32 v48, 16, v2
	v_and_b32_e32 v49, 0xffff0000, v2
	v_lshlrev_b32_e32 v50, 16, v3
	v_and_b32_e32 v51, 0xffff0000, v3
	s_waitcnt vmcnt(6)
; DI void unpack8(uint4 v, float* f) { f[0] = bflo(v.x); f[1] = bfhi(v.x); f[2] = bflo(v.y); f[3] = bfhi(v.y); f[4] = bflo(v.z); f[5] = bfhi(v.z); f[6] = bflo(v.w); f[7] = bfhi(v.w); }
; DI uint4 pack8(const float* f) { uint4 r; r.x = pk2(f[0], f[1]); r.y = pk2(f[2], f[3]); r.z = pk2(f[4], f[5]); r.w = pk2(f[6], f[7]); return r; }
; DI void ret_out_unit(const Params& p, int hf, int bl, int c, int hd, unsigned char* shm, int tid, bool dry = false) {
;     ...
;   for (int it = 0; it < 2; ++it) {
;     const int idx = tid + it * NTHR, j = idx >> 3, dg = idx & 7;
;     const bf16_t* base = projb + (size_t)(c * 128 + j) * NP;
;     float q1[8], q2[8], k1[8], k2[8];
;     unpack8(*(const uint4*)(base + C_RQ + hd * 128 + dg * 8), q1); unpack8(*(const uint4*)(base + C_RQ + hd * 128 + 64 + dg * 8), q2);
;     unpack8(*(const uint4*)(base + C_RK + hd * 128 + dg * 8), k1); unpack8(*(const uint4*)(base + C_RK + hd * 128 + 64 + dg * 8), k2);
;     float oq1[8], oq2[8], ok1[8], ok2[8];
; #pragma unroll
;     for (int e = 0; e < 8; ++e) {
;       const float2 t = cs[j * 64 + dg * 8 + e];
;       oq1[e] = q1[e] * t.x - q2[e] * t.y; oq2[e] = q1[e] * t.y + q2[e] * t.x;
;       ok1[e] = (k1[e] * t.x - k2[e] * t.y) * 0.08838834764831845f; ok2[e] = (k1[e] * t.y + k2[e] * t.x) * 0.08838834764831845f;
;     }
;     *(uint4*)(sQ + j * LD + dg * 8) = pack8(oq1); *(uint4*)(sQ + j * LD + 64 + dg * 8) = pack8(oq2);
;     *(uint4*)(sK + j * LD + dg * 8) = pack8(ok1); *(uint4*)(sK + j * LD + 64 + dg * 8) = pack8(ok2);
;     *(uint4*)(sVt + j * LD + dg * 16) = *(const uint4*)(base + C_RV + hd * 128 + dg * 16);
;     *(uint4*)(sVt + j * LD + dg * 16 + 8) = *(const uint4*)(base + C_RV + hd * 128 + dg * 16 + 8);
;   }
;   __syncthreads();
;   const int wid = tid >> 6, lane = tid & 63, fr = lane & 15, fq = lane >> 4;
;   const int i_row = 16 * wid + fr;
;   uint4 stv0, stv1, stv2, stv3; uint2 gv8[8];
;   {
;     const bf16_t* st = (const bf16_t*)(wsb + WS_RST) + (size_t)((bl * 64 + c) * 4 + hd) * 16384;
;     { const int e0 = tid >> 3, dg = tid & 7; stv0 = *(const uint4*)(st + e0 * 128 + dg * 16); stv1 = *(const uint4*)(st + e0 * 128 + dg * 16 + 8); stv2 = *(const uint4*)(st + (e0 + 64) * 128 + dg * 16); stv3 = *(const uint4*)(st + (e0 + 64) * 128 + dg * 16 + 8); }
	v_mov_b32_e32 v0, v152
	v_mov_b32_e32 v1, v153
	v_mov_b32_e32 v2, v154
	v_mov_b32_e32 v3, v155
	v_lshlrev_b32_e32 v52, 16, v0
	v_and_b32_e32 v53, 0xffff0000, v0
	v_lshl_or_b32 v0, v14, 6, v20
	v_lshlrev_b32_e32 v54, 16, v1
	v_and_b32_e32 v55, 0xffff0000, v1
	v_ashrrev_i32_e32 v1, 31, v0
	v_lshl_add_u64 v[10:11], v[0:1], 3, s[0:1]
	v_lshlrev_b32_e32 v56, 16, v2
	v_and_b32_e32 v57, 0xffff0000, v2
	v_lshlrev_b32_e32 v58, 16, v3
	v_and_b32_e32 v59, 0xffff0000, v3
	s_and_b32 s0, s5, 0x3ff00
	s_lshl_b32 s1, s7, 2
	s_or_b32 s0, s1, s0
	s_or_b32 s0, s0, s6
	s_lshl_b32 s0, s0, 14
	s_mov_b32 s1, s3
	s_lshl_b64 s[0:1], s[0:1], 1
	v_readlane_b32 s5, v253, 28
	s_add_u32 s0, s5, s0
	v_readlane_b32 s5, v253, 29
	s_addc_u32 s1, s5, s1
	s_waitcnt vmcnt(2)
	v_mov_b32_e32 v0, v156
	v_mov_b32_e32 v1, v157
	v_mov_b32_e32 v2, v158
	v_mov_b32_e32 v3, v159
	v_mov_b32_e32 v6, v204
	v_mov_b32_e32 v7, v205
	v_mov_b32_e32 v8, v206
	v_mov_b32_e32 v9, v207
	v_mov_b32_e32 v20, v208
	v_mov_b32_e32 v21, v209
	v_mov_b32_e32 v22, v210
	v_mov_b32_e32 v23, v211
	v_mov_b32_e32 v24, v212
	v_mov_b32_e32 v25, v213
	v_mov_b32_e32 v26, v214
	v_mov_b32_e32 v27, v215
	v_mul_f32_e32 v10, v25, v36
	v_fma_f32 v10, v24, v15, -v10
	v_mul_f32_e32 v11, v25, v15
	v_mul_f32_e32 v15, v25, v52
	v_mul_f32_e32 v25, v25, v44
	v_fmac_f32_e32 v25, v24, v52
	v_fmac_f32_e32 v11, v24, v36
	v_fma_f32 v15, v24, v44, -v15
	v_mul_f32_e32 v24, 0x3db504f3, v25
	v_mul_f32_e32 v25, v27, v37
	v_fma_f32 v25, v26, v28, -v25
	v_mul_f32_e32 v28, v27, v28
	v_mul_f32_e32 v36, v27, v53
	v_mul_f32_e32 v27, v27, v45
	v_fmac_f32_e32 v27, v26, v53
	v_fmac_f32_e32 v28, v26, v37
	v_fma_f32 v36, v26, v45, -v36
	v_mul_f32_e32 v26, 0x3db504f3, v27
	v_mul_f32_e32 v27, v21, v38
	v_fma_f32 v27, v20, v29, -v27
	v_mul_f32_e32 v29, v21, v29
	v_mul_f32_e32 v37, v21, v54
	v_mul_f32_e32 v21, v21, v46
	v_fmac_f32_e32 v21, v20, v54
	v_fmac_f32_e32 v29, v20, v38
	v_fma_f32 v37, v20, v46, -v37
	v_mul_f32_e32 v20, 0x3db504f3, v21
	v_mul_f32_e32 v21, v23, v39
	v_fma_f32 v21, v22, v30, -v21
	v_mul_f32_e32 v30, v23, v30
	v_mul_f32_e32 v38, v23, v55
	v_mul_f32_e32 v23, v23, v47
	v_fmac_f32_e32 v23, v22, v55
	v_fmac_f32_e32 v30, v22, v39
	v_fma_f32 v38, v22, v47, -v38
	v_mul_f32_e32 v22, 0x3db504f3, v23
	v_mul_f32_e32 v23, v7, v40
	v_fma_f32 v23, v6, v31, -v23
	v_mul_f32_e32 v31, v7, v31
	v_mul_f32_e32 v39, v7, v56
	v_mul_f32_e32 v7, v7, v48
	v_fmac_f32_e32 v7, v6, v56
	v_fmac_f32_e32 v31, v6, v40
	v_fma_f32 v39, v6, v48, -v39
	v_mul_f32_e32 v6, 0x3db504f3, v7
	v_mul_f32_e32 v7, v9, v41
	v_fma_f32 v7, v8, v33, -v7
	v_mul_f32_e32 v33, v9, v33
	v_mul_f32_e32 v40, v9, v57
	v_mul_f32_e32 v9, v9, v49
	v_fmac_f32_e32 v9, v8, v57
	v_fmac_f32_e32 v33, v8, v41
	v_fma_f32 v40, v8, v49, -v40
	v_mul_f32_e32 v8, 0x3db504f3, v9
	v_mul_f32_e32 v9, v1, v42
	v_fma_f32 v9, v0, v34, -v9
	v_mul_f32_e32 v34, v1, v34
	v_mul_f32_e32 v41, v1, v58
	v_mul_f32_e32 v1, v1, v50
	v_fmac_f32_e32 v34, v0, v42
	v_fma_f32 v41, v0, v50, -v41
	v_fmac_f32_e32 v1, v0, v58
	v_mul_f32_e32 v0, v3, v43
	v_fma_f32 v44, v2, v35, -v0
	v_mul_f32_e32 v0, v3, v59
	v_mul_f32_e32 v35, v3, v35
	v_fma_f32 v0, v2, v51, -v0
	v_fmac_f32_e32 v35, v2, v43
	v_mul_f32_e32 v43, 0x3db504f3, v0
	v_mul_f32_e32 v0, v3, v51
	v_fmac_f32_e32 v0, v2, v59
	v_mul_f32_e32 v42, 0x3db504f3, v1
	v_mul_f32_e32 v45, 0x3db504f3, v0
	v_cvt_pk_bf16_f32 v0, v10, v25
	v_cvt_pk_bf16_f32 v1, v27, v21
	v_cvt_pk_bf16_f32 v2, v23, v7
	v_mul_lo_u32 v7, v14, s66
	v_cvt_pk_bf16_f32 v3, v9, v44
	v_add3_u32 v9, 32, v7, v160
	ds_write_b128 v9, v[0:3]
	v_cvt_pk_bf16_f32 v0, v11, v28
	v_cvt_pk_bf16_f32 v1, v29, v30
	v_cvt_pk_bf16_f32 v2, v31, v33
	v_cvt_pk_bf16_f32 v3, v34, v35
	v_mul_f32_e32 v15, 0x3db504f3, v15
	v_mul_f32_e32 v36, 0x3db504f3, v36
	v_mul_f32_e32 v37, 0x3db504f3, v37
	v_mul_f32_e32 v38, 0x3db504f3, v38
	v_mul_f32_e32 v39, 0x3db504f3, v39
	v_mul_f32_e32 v40, 0x3db504f3, v40
	v_mul_f32_e32 v41, 0x3db504f3, v41
	ds_write_b128 v9, v[0:3] offset:128
	v_cvt_pk_bf16_f32 v0, v15, v36
	v_cvt_pk_bf16_f32 v1, v37, v38
	v_cvt_pk_bf16_f32 v2, v39, v40
	v_cvt_pk_bf16_f32 v3, v41, v43
	ds_write_b128 v9, v[0:3] offset:34816
	v_cvt_pk_bf16_f32 v0, v24, v26
	v_cvt_pk_bf16_f32 v1, v20, v22
	v_cvt_pk_bf16_f32 v2, v6, v8
	v_cvt_pk_bf16_f32 v3, v42, v45
	ds_write_b128 v9, v[0:3] offset:34944
	v_add_u32_e32 v6, v19, v7
	v_lshlrev_b32_e32 v8, 7, v18
	v_ashrrev_i32_e32 v9, 31, v8
	v_add_u32_e32 v18, s4, v68
	v_lshlrev_b32_e32 v34, 3, v75
	v_mov_b32_e32 v35, v161
	v_mul_lo_u32 v33, v68, s66
	v_add_u32_e32 v70, 32, v33
	v_lshlrev_b32_e32 v36, 2, v75
	s_waitcnt vmcnt(1)
	v_mov_b32_e32 v0, v216
	v_mov_b32_e32 v1, v217
	v_mov_b32_e32 v2, v218
	v_mov_b32_e32 v3, v219
	ds_write_b128 v6, v[0:3]
	s_waitcnt vmcnt(0)
	v_mov_b32_e32 v0, v220
	v_mov_b32_e32 v1, v221
	v_mov_b32_e32 v2, v222
	v_mov_b32_e32 v3, v223
	ds_write_b128 v6, v[0:3] offset:16
	v_lshl_add_u64 v[0:1], v[8:9], 1, s[0:1]
	v_add_u32_e32 v8, 0x2000, v8
	v_ashrrev_i32_e32 v9, 31, v8
	v_lshl_add_u64 v[8:9], v[8:9], 1, s[0:1]
	v_mad_i64_i32 v[16:17], s[0:1], v18, s65, v[16:17]
	v_lshl_add_u64 v[16:17], v[16:17], 0, s[2:3]
	v_lshlrev_b32_e32 v2, 4, v66
	v_lshl_add_u64 v[16:17], v[16:17], 0, v[34:35]
	s_mov_b64 s[0:1], 0x2400
	v_and_b32_e32 v2, 0x70, v2
	v_lshl_add_u64 v[48:49], v[16:17], 0, s[0:1]
	s_movk_i32 s0, 0x2000
	v_lshlrev_b32_e32 v160, 1, v2
	v_add_co_u32_e32 v16, vcc, s0, v16
	v_lshl_add_u64 v[4:5], v[0:1], 0, v[160:161]
	v_lshl_add_u64 v[12:13], v[8:9], 0, v[160:161]
	v_addc_co_u32_e32 v17, vcc, 0, v17, vcc
	s_waitcnt lgkmcnt(0)
	s_barrier
; DI unsigned pk2(float lo, float hi) { unsigned r; asm volatile("v_cvt_pk_bf16_f32 %0, %1, %2" : "=v"(r) : "v"(lo), "v"(hi)); return r; }
; DI f32x4 mmaT(bf16x8 a_m, bf16x8 b_n, f32x4 c) { return __builtin_amdgcn_mfma_f32_16x16x32_bf16(b_n, a_m, c, 0, 0, 0); }
; DI void ret_out_unit(const Params& p, int hf, int bl, int c, int hd, unsigned char* shm, int tid, bool dry = false) {
;     ...
;   const int wid = tid >> 6, lane = tid & 63, fr = lane & 15, fq = lane >> 4;
;   const int i_row = 16 * wid + fr;
;   uint4 stv0, stv1, stv2, stv3; uint2 gv8[8];
;   {
;     const bf16_t* st = (const bf16_t*)(wsb + WS_RST) + (size_t)((bl * 64 + c) * 4 + hd) * 16384;
;     { const int e0 = tid >> 3, dg = tid & 7; stv0 = *(const uint4*)(st + e0 * 128 + dg * 16); stv1 = *(const uint4*)(st + e0 * 128 + dg * 16 + 8); stv2 = *(const uint4*)(st + (e0 + 64) * 128 + dg * 16); stv3 = *(const uint4*)(st + (e0 + 64) * 128 + dg * 16 + 8); }
;     const bf16_t* gp0 = projb + (size_t)(c * 128 + i_row) * NP + C_RG + hd * 128 + 4 * fq;
; #pragma unroll
;     for (int n = 0; n < 8; ++n) gv8[n] = *(const uint2*)(gp0 + 16 * n);
;   }
;   {
;     bf16x8 aq[4];
; #pragma unroll
;     for (int ks = 0; ks < 4; ++ks) aq[ks] = ldf(sQ, LD, 16 * wid, 32 * ks, fr, fq);
; #pragma unroll
;     for (int n = 0; n < 8; ++n) {
;       if (n <= (wid | 1)) {
;         uint2 w; w.x = 0u; w.y = 0u;
;         if (n <= wid) {
;           f32x4 s = (f32x4){0.f, 0.f, 0.f, 0.f};
; #pragma unroll
;           for (int ks = 0; ks < 4; ++ks) s = mmaT(aq[ks], ldf(sK, LD, 16 * n, 32 * ks, fr, fq), s);
;           float r[4];
; #pragma unroll
;           for (int j = 0; j < 4; ++j) { const int d = i_row - (16 * n + 4 * fq + j); r[j] = (d >= 0) ? s[j] * __expf(lg * (float)d) : 0.f; }
;           w.x = pk2(r[0], r[1]); w.y = pk2(r[2], r[3]);
	global_load_dwordx4 v[0:3], v[4:5], off offset:16
	s_nop 0
	global_load_dwordx4 v[4:7], v[4:5], off
	s_nop 0
	global_load_dwordx4 v[8:11], v[12:13], off offset:16
	s_nop 0
	global_load_dwordx4 v[12:15], v[12:13], off
	s_nop 0
	global_load_dwordx2 v[64:65], v[16:17], off offset:1024
	global_load_dwordx2 v[62:63], v[48:49], off offset:32
	global_load_dwordx2 v[60:61], v[48:49], off offset:64
	global_load_dwordx2 v[58:59], v[48:49], off offset:96
	global_load_dwordx2 v[56:57], v[48:49], off offset:128
	global_load_dwordx2 v[54:55], v[48:49], off offset:160
	global_load_dwordx2 v[52:53], v[48:49], off offset:192
	global_load_dwordx2 v[50:51], v[48:49], off offset:224
	s_mov_b32 s0, 0x800000
	v_cmp_gt_f32_e32 vcc, s0, v32
	s_and_b64 s[0:1], vcc, exec
	s_cselect_b32 s0, 32, 0
	v_ldexp_f32 v32, v32, s0
	v_log_f32_e32 v32, v32
	v_and_b32_e32 v35, 48, v66
	v_add_u32_e32 v16, v70, v35
	ds_read_b128 v[28:31], v16
	ds_read_b128 v[24:27], v16 offset:64
	ds_read_b128 v[20:23], v16 offset:128
	ds_read_b128 v[16:19], v16 offset:192
	v_mul_f32_e32 v37, 0x3f317217, v32
	s_mov_b32 s0, 0x3f317217
	v_fma_f32 v37, v32, s0, -v37
	v_fmac_f32_e32 v37, 0x3377d1cf, v32
	s_mov_b32 s0, 0x7f800000
	v_fmac_f32_e32 v37, 0x3f317217, v32
	v_cmp_lt_f32_e64 s[0:1], |v32|, s0
	v_add_u32_e32 v38, 32, v35
	s_nop 0
	v_cndmask_b32_e64 v32, v32, v37, s[0:1]
	v_cndmask_b32_e32 v37, 0, v201, vcc
	v_readlane_b32 s0, v254, 1
	v_sub_f32_e32 v69, v32, v37
	v_cmp_lt_i32_e32 vcc, -1, v73
	v_add3_u32 v37, s0, v33, v34
	s_and_saveexec_b64 s[0:1], vcc
	s_cbranch_execz .LBB0_439
	v_mad_u32_u24 v39, v74, s66, v38
	ds_read_b128 v[32:35], v39 offset:34816
	ds_read_b128 v[40:43], v39 offset:34880
	s_waitcnt lgkmcnt(1)
	v_mfma_f32_16x16x32_bf16 v[32:35], v[32:35], v[28:31], 0
	s_waitcnt lgkmcnt(0)
	v_mfma_f32_16x16x32_bf16 v[32:35], v[40:43], v[24:27], v[32:35]
	ds_read_b128 v[40:43], v39 offset:34944
	s_waitcnt lgkmcnt(0)
	v_mfma_f32_16x16x32_bf16 v[32:35], v[40:43], v[20:23], v[32:35]
	ds_read_b128 v[40:43], v39 offset:35008
	v_sub_u32_e32 v39, v68, v36
	v_cmp_lt_i32_e32 vcc, -1, v39
	v_cvt_f32_u32_e32 v39, v39
	s_waitcnt lgkmcnt(0)
	v_mfma_f32_16x16x32_bf16 v[32:35], v[40:43], v[16:19], v[32:35]
	v_mul_f32_e32 v39, v69, v39
	v_mul_f32_e32 v39, 0x3fb8aa3b, v39
	v_exp_f32_e32 v39, v39
	s_nop 4
	v_mul_f32_e32 v32, v39, v32
	v_xad_u32 v39, v36, -1, v68
	v_cndmask_b32_e32 v32, 0, v32, vcc
	v_cmp_lt_i32_e32 vcc, -1, v39
	v_cvt_f32_u32_e32 v39, v39
	v_mul_f32_e32 v39, v69, v39
	v_mul_f32_e32 v39, 0x3fb8aa3b, v39
	v_exp_f32_e32 v39, v39
	s_nop 0
	v_mul_f32_e32 v33, v39, v33
	v_or_b32_e32 v39, 2, v36
	v_sub_u32_e32 v39, v68, v39
	v_cndmask_b32_e32 v33, 0, v33, vcc
	v_cmp_lt_i32_e32 vcc, -1, v39
	v_cvt_f32_u32_e32 v39, v39
	v_cvt_pk_bf16_f32 v32, v32, v33
	v_mul_f32_e32 v39, v69, v39
	v_mul_f32_e32 v39, 0x3fb8aa3b, v39
	v_exp_f32_e32 v39, v39
	s_nop 0
	v_mul_f32_e32 v34, v39, v34
	v_or_b32_e32 v39, 3, v36
	v_sub_u32_e32 v39, v68, v39
	v_cndmask_b32_e32 v34, 0, v34, vcc
	v_cmp_lt_i32_e32 vcc, -1, v39
	v_cvt_f32_u32_e32 v39, v39
	v_mul_f32_e32 v39, v69, v39
	v_mul_f32_e32 v39, 0x3fb8aa3b, v39
	v_exp_f32_e32 v39, v39
	s_nop 0
	v_mul_f32_e32 v35, v39, v35
	v_cndmask_b32_e32 v35, 0, v35, vcc
	v_cvt_pk_bf16_f32 v33, v34, v35
	ds_write_b64 v37, v[32:33]
	v_cmp_lt_u32_e32 vcc, 63, v66
	v_mov_b32_e32 v32, 0
	v_mov_b32_e32 v33, 0
	s_and_saveexec_b64 s[4:5], vcc
	s_cbranch_execz .LBB0_438
	v_add_u32_e32 v39, v38, v71
	ds_read_b128 v[32:35], v39 offset:39168
	ds_read_b128 v[40:43], v39 offset:39232
	s_waitcnt lgkmcnt(1)
	v_mfma_f32_16x16x32_bf16 v[32:35], v[32:35], v[28:31], 0
	s_waitcnt lgkmcnt(0)
	v_mfma_f32_16x16x32_bf16 v[32:35], v[40:43], v[24:27], v[32:35]
	ds_read_b128 v[40:43], v39 offset:39296
	s_waitcnt lgkmcnt(0)
	v_mfma_f32_16x16x32_bf16 v[32:35], v[40:43], v[20:23], v[32:35]
	ds_read_b128 v[40:43], v39 offset:39360
	v_or_b32_e32 v39, 16, v36
	v_sub_u32_e32 v39, v68, v39
	v_cmp_lt_i32_e32 vcc, -1, v39
	v_cvt_f32_u32_e32 v39, v39
	s_waitcnt lgkmcnt(0)
	v_mfma_f32_16x16x32_bf16 v[32:35], v[40:43], v[16:19], v[32:35]
	v_mul_f32_e32 v39, v69, v39
	v_mul_f32_e32 v39, 0x3fb8aa3b, v39
	v_exp_f32_e32 v39, v39
	s_nop 4
	v_mul_f32_e32 v32, v39, v32
	v_or_b32_e32 v39, 17, v36
	v_sub_u32_e32 v39, v68, v39
	v_cndmask_b32_e32 v32, 0, v32, vcc
	v_cmp_lt_i32_e32 vcc, -1, v39
	v_cvt_f32_u32_e32 v39, v39
	v_mul_f32_e32 v39, v69, v39
	v_mul_f32_e32 v39, 0x3fb8aa3b, v39
	v_exp_f32_e32 v39, v39
	s_nop 0
	v_mul_f32_e32 v33, v39, v33
	v_or_b32_e32 v39, 18, v36
	v_sub_u32_e32 v39, v68, v39
	v_cndmask_b32_e32 v33, 0, v33, vcc
	v_cmp_lt_i32_e32 vcc, -1, v39
	v_cvt_f32_u32_e32 v39, v39
	v_cvt_pk_bf16_f32 v32, v32, v33
	v_mul_f32_e32 v39, v69, v39
	v_mul_f32_e32 v39, 0x3fb8aa3b, v39
	v_exp_f32_e32 v39, v39
	s_nop 0
	v_mul_f32_e32 v34, v39, v34
	v_or_b32_e32 v39, 19, v36
	v_sub_u32_e32 v39, v68, v39
	v_cndmask_b32_e32 v34, 0, v34, vcc
	v_cmp_lt_i32_e32 vcc, -1, v39
	v_cvt_f32_u32_e32 v39, v39
	v_mul_f32_e32 v39, v69, v39
	v_mul_f32_e32 v39, 0x3fb8aa3b, v39
	v_exp_f32_e32 v39, v39
	s_nop 0
	v_mul_f32_e32 v35, v39, v35
	v_cndmask_b32_e32 v35, 0, v35, vcc
	v_cvt_pk_bf16_f32 v33, v34, v35

; DI void unpack8(uint4 v, float* f) { f[0] = bflo(v.x); f[1] = bfhi(v.x); f[2] = bflo(v.y); f[3] = bfhi(v.y); f[4] = bflo(v.z); f[5] = bfhi(v.z); f[6] = bflo(v.w); f[7] = bfhi(v.w); }
; #define otid() otid_(wbase)
; DI void fox_unit(const Params& p, int hf, int bl, int fh, int qb, unsigned char* shm, int tid, bool dry = false) {
;   unsigned char* wsb = ows(p);
;   constexpr int STG = 64 * 72 * 2 * 2 + 256;
;   bf16_t* projb = (bf16_t*)(wsb + WS_PROJ) + (size_t)bl * SEQ * NP;
;   const float* F = (const float*)(wsb + WS_FC) + (size_t)(bl * 8 + fh) * SEQ;
;   const int wid = tid >> 6, lane = tid & 63, fr = lane & 15, fq = lane >> 4;
;   const int q0 = qb * 256, qg0 = q0 + wid * 32 + fr;
;   bf16x8 qf[2][2];
; #pragma unroll
;   for (int mi = 0; mi < 2; ++mi)
; #pragma unroll
;     for (int ks = 0; ks < 2; ++ks) {
;       const uint4 raw = *(const uint4*)(projb + (size_t)(qg0 + 16 * mi) * NP + C_FQ + fh * 64 + ks * 32 + fq * 8);
;       qf[mi][ks] = __builtin_bit_cast(bf16x8, raw);
;     }
;   float qmax2 = 0.f;
; #pragma unroll
;   for (int mi = 0; mi < 2; ++mi) {
;     float ssum = 0.f;
; #pragma unroll
;     for (int ks = 0; ks < 2; ++ks) { float f[8]; unpack8(__builtin_bit_cast(uint4, qf[mi][ks]), f);
; #pragma unroll
;       for (int z = 0; z < 8; ++z) ssum += f[z] * f[z]; }
;     ssum += shx(ssum, 16, lane); ssum += shx(ssum, 32, lane);
;     qmax2 = fmaxf(qmax2, ssum);
;   }
; #pragma unroll
;   for (int o_ = 8; o_ >= 1; o_ >>= 1) qmax2 = fmaxf(qmax2, shx(qmax2, o_, lane));
;   float* sRed = (float*)(shm + 2 * STG);
;   if (lane == 0) sRed[wid] = qmax2;
; __global__ void __launch_bounds__(NTHR) mega(Params p) {
;     ...
;           if (u < 256) { fox_unit(p, hf, (u >> 3) & 1, u & 7, 31 - (u >> 4), shm, otid()); }
;           else if (u < 448) {
;             scan_unit(p, hf, u - 256, otid());
;             asm volatile("s_waitcnt vmcnt(0)" ::: "memory");
;             __syncthreads();
;             if (otid() == 0) { __builtin_amdgcn_fence(__ATOMIC_RELEASE, "agent"); asm volatile("s_waitcnt vmcnt(0)" ::: "memory"); __hip_atomic_fetch_add(dep, 1, __ATOMIC_RELAXED, __HIP_MEMORY_SCOPE_AGENT); }
;           }
;           else if (u < 576) { const int k = u - 448; ssd_out_unit(p, layer, hf, k >> 6, k & 63, shm, otid()); }
;           else if (u < 832) { const int k = u - 576 + 256; fox_unit(p, hf, (k >> 3) & 1, k & 7, 31 - (k >> 4), shm, otid()); }
.LBB0_468:
	s_and_b64 vcc, exec, s[0:1]
	s_cbranch_vccz .LBB0_499
	v_readlane_b32 s0, v254, 60
	s_addk_i32 s0, 0xff40
	s_lshr_b32 s0, s0, 4
	s_sub_i32 s4, 31, s0
	s_bfe_i32 s0, s23, 0x10003
	s_and_b32 s0, s0, 0x6800000
	v_mov_b32_e32 v205, v163
	s_add_u32 s6, s38, s0
	s_addc_u32 s7, s39, 0
	v_ashrrev_i32_e32 v26, 6, v205
	s_lshl_b32 s5, s4, 8
	v_and_b32_e32 v27, 15, v205
	v_lshl_add_u32 v28, v26, 5, s5
	s_lshl_b32 s0, s23, 6
	v_or_b32_e32 v206, v28, v27
	s_and_b32 s2, s0, 0x1c0
	v_mov_b64_e32 v[8:9], s[6:7]
	v_mad_i64_i32 v[126:127], s[0:1], v206, s65, v[8:9]
	s_lshl_b32 s2, s2, 1
	v_lshl_add_u64 v[0:1], v[126:127], 0, s[2:3]
	v_and_b32_e32 v24, 48, v205
	v_mov_b32_e32 v25, v161
	v_lshl_add_u64 v[0:1], v[0:1], 0, v[24:25]
	s_mov_b64 s[10:11], 0x1800
	s_movk_i32 s8, 0x1000
	v_lshl_add_u64 v[4:5], v[0:1], 0, s[10:11]
	v_add_co_u32_e32 v0, vcc, s8, v0
	v_or_b32_e32 v207, 16, v206
	s_nop 0
	v_addc_co_u32_e32 v1, vcc, 0, v1, vcc
	global_load_dwordx4 v[0:3], v[0:1], off offset:2048
	s_nop 0
	global_load_dwordx4 v[4:7], v[4:5], off offset:64
	v_mad_i64_i32 v[108:109], s[0:1], v207, s65, v[8:9]
	v_lshl_add_u64 v[8:9], v[108:109], 0, s[2:3]
	v_lshl_add_u64 v[8:9], v[8:9], 0, v[24:25]
	v_lshl_add_u64 v[12:13], v[8:9], 0, s[10:11]
	v_add_co_u32_e32 v8, vcc, s8, v8
	v_and_b32_e32 v16, 63, v205
	s_nop 0
	v_addc_co_u32_e32 v9, vcc, 0, v9, vcc
	global_load_dwordx4 v[8:11], v[8:9], off offset:2048
	s_nop 0
	global_load_dwordx4 v[12:15], v[12:13], off offset:64
	v_lshlrev_b32_e32 v18, 2, v16
	v_xor_b32_e32 v204, 64, v18
	v_xor_b32_e32 v169, 0x80, v18
	v_cmp_eq_u32_e32 vcc, 0, v16
	v_lshl_add_u32 v16, v26, 2, 32
	s_waitcnt vmcnt(3)
	v_and_b32_e32 v19, 0xffff0000, v0
	v_lshlrev_b32_e32 v17, 16, v0
	v_mul_f32_e32 v19, v19, v19
	v_lshlrev_b32_e32 v20, 16, v1
	v_fmac_f32_e32 v19, v17, v17
	v_and_b32_e32 v21, 0xffff0000, v1
	v_fmac_f32_e32 v19, v20, v20
	v_lshlrev_b32_e32 v22, 16, v2
	v_fmac_f32_e32 v19, v21, v21
	v_and_b32_e32 v23, 0xffff0000, v2
	v_fmac_f32_e32 v19, v22, v22
	v_lshlrev_b32_e32 v25, 16, v3
	v_fmac_f32_e32 v19, v23, v23
	v_and_b32_e32 v29, 0xffff0000, v3
	v_fmac_f32_e32 v19, v25, v25
	v_fmac_f32_e32 v19, v29, v29
	s_waitcnt vmcnt(2)
	v_lshlrev_b32_e32 v17, 16, v4
	v_and_b32_e32 v20, 0xffff0000, v4
	v_fmac_f32_e32 v19, v17, v17
	v_lshlrev_b32_e32 v21, 16, v5
	v_fmac_f32_e32 v19, v20, v20
	v_and_b32_e32 v22, 0xffff0000, v5
	v_fmac_f32_e32 v19, v21, v21
	v_lshlrev_b32_e32 v23, 16, v6
	v_fmac_f32_e32 v19, v22, v22
	v_and_b32_e32 v25, 0xffff0000, v6
	v_fmac_f32_e32 v19, v23, v23
	v_lshlrev_b32_e32 v29, 16, v7
	v_fmac_f32_e32 v19, v25, v25
	v_and_b32_e32 v30, 0xffff0000, v7
	v_fmac_f32_e32 v19, v29, v29
	v_fmac_f32_e32 v19, v30, v30
	ds_bpermute_b32 v17, v204, v19
	s_waitcnt vmcnt(1)
	v_and_b32_e32 v20, 0xffff0000, v8
	v_mul_f32_e32 v20, v20, v20
	v_lshlrev_b32_e32 v21, 16, v9
	v_and_b32_e32 v22, 0xffff0000, v9
	s_waitcnt lgkmcnt(0)
	v_add_f32_e32 v17, v19, v17
	ds_bpermute_b32 v19, v169, v17
	v_lshlrev_b32_e32 v23, 16, v10
	v_and_b32_e32 v25, 0xffff0000, v10
	v_lshlrev_b32_e32 v29, 16, v11
	v_and_b32_e32 v30, 0xffff0000, v11
	s_waitcnt lgkmcnt(0)
	v_add_f32_e32 v17, v17, v19
	v_lshlrev_b32_e32 v19, 16, v8
	v_fmac_f32_e32 v20, v19, v19
	v_fmac_f32_e32 v20, v21, v21
	v_fmac_f32_e32 v20, v22, v22
	v_fmac_f32_e32 v20, v23, v23
	v_fmac_f32_e32 v20, v25, v25
	v_fmac_f32_e32 v20, v29, v29
	v_fmac_f32_e32 v20, v30, v30
	s_waitcnt vmcnt(0)
	v_lshlrev_b32_e32 v19, 16, v12
	v_and_b32_e32 v21, 0xffff0000, v12
	v_fmac_f32_e32 v20, v19, v19
	v_lshlrev_b32_e32 v22, 16, v13
	v_fmac_f32_e32 v20, v21, v21
	v_and_b32_e32 v23, 0xffff0000, v13
	v_fmac_f32_e32 v20, v22, v22
	v_lshlrev_b32_e32 v25, 16, v14
	v_fmac_f32_e32 v20, v23, v23
	v_and_b32_e32 v29, 0xffff0000, v14
	v_fmac_f32_e32 v20, v25, v25
	v_lshlrev_b32_e32 v30, 16, v15
	v_fmac_f32_e32 v20, v29, v29
	v_and_b32_e32 v31, 0xffff0000, v15
	v_fmac_f32_e32 v20, v30, v30
	v_fmac_f32_e32 v20, v31, v31
	ds_bpermute_b32 v19, v204, v20
	s_waitcnt lgkmcnt(0)
	v_add_f32_e32 v19, v20, v19
	ds_bpermute_b32 v20, v169, v19
	s_waitcnt lgkmcnt(0)
	v_add_f32_e32 v19, v19, v20
	v_max3_f32 v17, v17, 0, v19
	v_xor_b32_e32 v19, 32, v18
	ds_bpermute_b32 v19, v19, v17
	s_waitcnt lgkmcnt(0)
	v_max_f32_e32 v19, v19, v19
	v_max_f32_e32 v17, v17, v19
	v_xor_b32_e32 v19, 16, v18
	ds_bpermute_b32 v19, v19, v17
	s_waitcnt lgkmcnt(0)
	v_max_f32_e32 v19, v19, v19
	v_max_f32_e32 v17, v17, v19
	v_xor_b32_e32 v19, 8, v18
	ds_bpermute_b32 v19, v19, v17
	v_xor_b32_e32 v18, 4, v18
	s_waitcnt lgkmcnt(0)
	v_max_f32_e32 v19, v19, v19
	v_max_f32_e32 v17, v17, v19
	ds_bpermute_b32 v18, v18, v17
	s_and_saveexec_b64 s[0:1], vcc
	s_cbranch_execz .LBB0_471
	s_waitcnt lgkmcnt(0)
	v_max_f32_e32 v18, v18, v18
	v_max_f32_e32 v17, v17, v17
	v_max_f32_e32 v17, v17, v18
	ds_write_b32 v16, v17 offset:37376
